# v106: v99 with write-through (sc1) x_new stores in the folded residual epilogues (x is not re-read before the next residual step; less dirty data for the grid barrier's L2 write-back)
# speedup vs baseline: 1.0062x; 1.0052x over previous
.Lrf_bar:
	s_barrier
	global_load_dwordx4 v[200:203], v253, s[10:11] offset:0
	global_load_dwordx4 v[204:207], v253, s[10:11] offset:256
	global_load_dwordx4 v[208:211], v253, s[10:11] offset:512
	global_load_dwordx4 v[212:215], v253, s[10:11] offset:768
	global_load_dwordx4 v[216:219], v253, s[10:11] offset:2048
	global_load_dwordx4 v[220:223], v253, s[10:11] offset:2304
	global_load_dwordx4 v[240:243], v253, s[10:11] offset:2560
	global_load_dwordx4 v[244:247], v253, s[10:11] offset:2816
	v_lshl_add_u32 v251, v236, 2, s68
	v_lshlrev_b32_e32 v251, 1, v251
	v_add_u32_e32 v249, s67, v235
	v_mul_u32_u24_e32 v249, 0x210, v249
	v_add_u32_e32 v251, v251, v249
	v_add_u32_e32 v252, 0x10800, v251
	s_mov_b32 s2, 0x3a800000
	s_waitcnt vmcnt(7)
	v_add_f32_e32 v200, v200, v201
	v_add_f32_e32 v202, v202, v203
	v_add_f32_e32 v200, v200, v202
	v_fma_f32 v200, v200, s2, v167
	v_rsq_f32_e32 v200, v200
	s_waitcnt vmcnt(6)
	v_add_f32_e32 v204, v204, v205
	v_add_f32_e32 v206, v206, v207
	v_add_f32_e32 v204, v204, v206
	v_fma_f32 v204, v204, s2, v167
	v_rsq_f32_e32 v204, v204
	s_waitcnt vmcnt(5)
	v_add_f32_e32 v208, v208, v209
	v_add_f32_e32 v210, v210, v211
	v_add_f32_e32 v208, v208, v210
	v_fma_f32 v208, v208, s2, v167
	v_rsq_f32_e32 v208, v208
	s_waitcnt vmcnt(4)
	v_add_f32_e32 v212, v212, v213
	v_add_f32_e32 v214, v214, v215
	v_add_f32_e32 v212, v212, v214
	v_fma_f32 v212, v212, s2, v167
	v_rsq_f32_e32 v212, v212
	s_waitcnt vmcnt(3)
	v_add_f32_e32 v216, v216, v217
	v_add_f32_e32 v218, v218, v219
	v_add_f32_e32 v216, v216, v218
	v_fma_f32 v216, v216, s2, v167
	v_rsq_f32_e32 v216, v216
	s_waitcnt vmcnt(2)
	v_add_f32_e32 v220, v220, v221
	v_add_f32_e32 v222, v222, v223
	v_add_f32_e32 v220, v220, v222
	v_fma_f32 v220, v220, s2, v167
	v_rsq_f32_e32 v220, v220
	s_waitcnt vmcnt(1)
	v_add_f32_e32 v240, v240, v241
	v_add_f32_e32 v242, v242, v243
	v_add_f32_e32 v240, v240, v242
	v_fma_f32 v240, v240, s2, v167
	v_rsq_f32_e32 v240, v240
	s_waitcnt vmcnt(0)
	v_add_f32_e32 v244, v244, v245
	v_add_f32_e32 v246, v246, v247
	v_add_f32_e32 v244, v244, v246
	v_fma_f32 v244, v244, s2, v167
	v_rsq_f32_e32 v244, v244
	s_nop 0
	v_readlane_b32 s8, v254, 61
	s_cmp_eq_u32 s8, 34
	s_cbranch_scc1 .Lrf_fin2
	global_store_dwordx4 v248, v[126:129], s[100:101] offset:0 sc1
	global_store_dwordx4 v248, v[122:125], s[100:101] offset:64 sc1
	global_store_dwordx4 v248, v[118:121], s[100:101] offset:512 sc1
	global_store_dwordx4 v248, v[114:117], s[100:101] offset:576 sc1
	s_nop 1
	v_mul_f32_e32 v126, v126, v200
	v_mul_f32_e32 v127, v127, v200
	v_mul_f32_e32 v128, v128, v200
	v_mul_f32_e32 v129, v129, v200
	v_fma_f32 v126, v126, v146, v162
	v_fma_f32 v127, v127, v147, v163
	v_fma_f32 v128, v128, v148, v164
	v_fma_f32 v129, v129, v149, v165
	v_cvt_pk_bf16_f32 v126, v126, v127
	v_cvt_pk_bf16_f32 v127, v128, v129
	v_mul_f32_e32 v122, v122, v200
	v_mul_f32_e32 v123, v123, v200
	v_mul_f32_e32 v124, v124, v200
	v_mul_f32_e32 v125, v125, v200
	v_fma_f32 v122, v122, v150, v188
	v_fma_f32 v123, v123, v151, v189
	v_fma_f32 v124, v124, v152, v190
	v_fma_f32 v125, v125, v153, v191
	v_cvt_pk_bf16_f32 v122, v122, v123
	v_cvt_pk_bf16_f32 v123, v124, v125
	v_mul_f32_e32 v118, v118, v200
	v_mul_f32_e32 v119, v119, v200
	v_mul_f32_e32 v120, v120, v200
	v_mul_f32_e32 v121, v121, v200
	v_fma_f32 v118, v118, v154, v192
	v_fma_f32 v119, v119, v155, v193
	v_fma_f32 v120, v120, v156, v194
	v_fma_f32 v121, v121, v157, v195
	v_cvt_pk_bf16_f32 v118, v118, v119
	v_cvt_pk_bf16_f32 v119, v120, v121
	v_mul_f32_e32 v114, v114, v200
	v_mul_f32_e32 v115, v115, v200
	v_mul_f32_e32 v116, v116, v200
	v_mul_f32_e32 v117, v117, v200
	v_fma_f32 v114, v114, v158, v196
	v_fma_f32 v115, v115, v159, v197
	v_fma_f32 v116, v116, v160, v198
	v_fma_f32 v117, v117, v161, v199
	v_cvt_pk_bf16_f32 v114, v114, v115
	v_cvt_pk_bf16_f32 v115, v116, v117
	ds_write_b64 v251, v[126:127] offset:0
	ds_write_b64 v251, v[122:123] offset:32
	ds_write_b64 v251, v[118:119] offset:256
	ds_write_b64 v251, v[114:115] offset:288
	s_add_u32 s8, s100, 0x10000
	s_addc_u32 s9, s101, 0
	global_store_dwordx4 v248, v[110:113], s[8:9] offset:0 sc1
	global_store_dwordx4 v248, v[106:109], s[8:9] offset:64 sc1
	global_store_dwordx4 v248, v[102:105], s[8:9] offset:512 sc1
	global_store_dwordx4 v248, v[98:101], s[8:9] offset:576 sc1
	s_nop 1
	v_mul_f32_e32 v110, v110, v204
	v_mul_f32_e32 v111, v111, v204
	v_mul_f32_e32 v112, v112, v204
	v_mul_f32_e32 v113, v113, v204
	v_fma_f32 v110, v110, v146, v162
	v_fma_f32 v111, v111, v147, v163
	v_fma_f32 v112, v112, v148, v164
	v_fma_f32 v113, v113, v149, v165
	v_cvt_pk_bf16_f32 v110, v110, v111
	v_cvt_pk_bf16_f32 v111, v112, v113
	v_mul_f32_e32 v106, v106, v204
	v_mul_f32_e32 v107, v107, v204
	v_mul_f32_e32 v108, v108, v204
	v_mul_f32_e32 v109, v109, v204
	v_fma_f32 v106, v106, v150, v188
	v_fma_f32 v107, v107, v151, v189
	v_fma_f32 v108, v108, v152, v190
	v_fma_f32 v109, v109, v153, v191
	v_cvt_pk_bf16_f32 v106, v106, v107
	v_cvt_pk_bf16_f32 v107, v108, v109
	v_mul_f32_e32 v102, v102, v204
	v_mul_f32_e32 v103, v103, v204
	v_mul_f32_e32 v104, v104, v204
	v_mul_f32_e32 v105, v105, v204
	v_fma_f32 v102, v102, v154, v192
	v_fma_f32 v103, v103, v155, v193
	v_fma_f32 v104, v104, v156, v194
	v_fma_f32 v105, v105, v157, v195
	v_cvt_pk_bf16_f32 v102, v102, v103
	v_cvt_pk_bf16_f32 v103, v104, v105
	v_mul_f32_e32 v98, v98, v204
	v_mul_f32_e32 v99, v99, v204
	v_mul_f32_e32 v100, v100, v204
	v_mul_f32_e32 v101, v101, v204
	v_fma_f32 v98, v98, v158, v196
	v_fma_f32 v99, v99, v159, v197
	v_fma_f32 v100, v100, v160, v198
	v_fma_f32 v101, v101, v161, v199
	v_cvt_pk_bf16_f32 v98, v98, v99
	v_cvt_pk_bf16_f32 v99, v100, v101
	ds_write_b64 v251, v[110:111] offset:8448
	ds_write_b64 v251, v[106:107] offset:8480
	ds_write_b64 v251, v[102:103] offset:8704
	ds_write_b64 v251, v[98:99] offset:8736
	s_add_u32 s8, s100, 0x20000
	s_addc_u32 s9, s101, 0
	global_store_dwordx4 v248, v[94:97], s[8:9] offset:0 sc1
	global_store_dwordx4 v248, v[90:93], s[8:9] offset:64 sc1
	global_store_dwordx4 v248, v[86:89], s[8:9] offset:512 sc1
	global_store_dwordx4 v248, v[82:85], s[8:9] offset:576 sc1
	s_nop 1
	v_mul_f32_e32 v94, v94, v208
	v_mul_f32_e32 v95, v95, v208
	v_mul_f32_e32 v96, v96, v208
	v_mul_f32_e32 v97, v97, v208
	v_fma_f32 v94, v94, v146, v162
	v_fma_f32 v95, v95, v147, v163
	v_fma_f32 v96, v96, v148, v164
	v_fma_f32 v97, v97, v149, v165
	v_cvt_pk_bf16_f32 v94, v94, v95
	v_cvt_pk_bf16_f32 v95, v96, v97
	v_mul_f32_e32 v90, v90, v208
	v_mul_f32_e32 v91, v91, v208
	v_mul_f32_e32 v92, v92, v208
	v_mul_f32_e32 v93, v93, v208
	v_fma_f32 v90, v90, v150, v188
	v_fma_f32 v91, v91, v151, v189
	v_fma_f32 v92, v92, v152, v190
	v_fma_f32 v93, v93, v153, v191
	v_cvt_pk_bf16_f32 v90, v90, v91
	v_cvt_pk_bf16_f32 v91, v92, v93
	v_mul_f32_e32 v86, v86, v208
	v_mul_f32_e32 v87, v87, v208
	v_mul_f32_e32 v88, v88, v208
	v_mul_f32_e32 v89, v89, v208
	v_fma_f32 v86, v86, v154, v192
	v_fma_f32 v87, v87, v155, v193
	v_fma_f32 v88, v88, v156, v194
	v_fma_f32 v89, v89, v157, v195
	v_cvt_pk_bf16_f32 v86, v86, v87
	v_cvt_pk_bf16_f32 v87, v88, v89
	v_mul_f32_e32 v82, v82, v208
	v_mul_f32_e32 v83, v83, v208
	v_mul_f32_e32 v84, v84, v208
	v_mul_f32_e32 v85, v85, v208
	v_fma_f32 v82, v82, v158, v196
	v_fma_f32 v83, v83, v159, v197
	v_fma_f32 v84, v84, v160, v198
	v_fma_f32 v85, v85, v161, v199
	v_cvt_pk_bf16_f32 v82, v82, v83
	v_cvt_pk_bf16_f32 v83, v84, v85
	ds_write_b64 v251, v[94:95] offset:16896
	ds_write_b64 v251, v[90:91] offset:16928
	ds_write_b64 v251, v[86:87] offset:17152
	ds_write_b64 v251, v[82:83] offset:17184
	s_add_u32 s8, s100, 0x30000
	s_addc_u32 s9, s101, 0
	global_store_dwordx4 v248, v[78:81], s[8:9] offset:0 sc1
	global_store_dwordx4 v248, v[74:77], s[8:9] offset:64 sc1
	global_store_dwordx4 v248, v[70:73], s[8:9] offset:512 sc1
	global_store_dwordx4 v248, v[66:69], s[8:9] offset:576 sc1
	s_nop 1
	v_mul_f32_e32 v78, v78, v212
	v_mul_f32_e32 v79, v79, v212
	v_mul_f32_e32 v80, v80, v212
	v_mul_f32_e32 v81, v81, v212
	v_fma_f32 v78, v78, v146, v162
	v_fma_f32 v79, v79, v147, v163
	v_fma_f32 v80, v80, v148, v164
	v_fma_f32 v81, v81, v149, v165
	v_cvt_pk_bf16_f32 v78, v78, v79
	v_cvt_pk_bf16_f32 v79, v80, v81
	v_mul_f32_e32 v74, v74, v212
	v_mul_f32_e32 v75, v75, v212
	v_mul_f32_e32 v76, v76, v212
	v_mul_f32_e32 v77, v77, v212
	v_fma_f32 v74, v74, v150, v188
	v_fma_f32 v75, v75, v151, v189
	v_fma_f32 v76, v76, v152, v190
	v_fma_f32 v77, v77, v153, v191
	v_cvt_pk_bf16_f32 v74, v74, v75
	v_cvt_pk_bf16_f32 v75, v76, v77
	v_mul_f32_e32 v70, v70, v212
	v_mul_f32_e32 v71, v71, v212
	v_mul_f32_e32 v72, v72, v212
	v_mul_f32_e32 v73, v73, v212
	v_fma_f32 v70, v70, v154, v192
	v_fma_f32 v71, v71, v155, v193
	v_fma_f32 v72, v72, v156, v194
	v_fma_f32 v73, v73, v157, v195
	v_cvt_pk_bf16_f32 v70, v70, v71
	v_cvt_pk_bf16_f32 v71, v72, v73
	v_mul_f32_e32 v66, v66, v212
	v_mul_f32_e32 v67, v67, v212
	v_mul_f32_e32 v68, v68, v212
	v_mul_f32_e32 v69, v69, v212
	v_fma_f32 v66, v66, v158, v196
	v_fma_f32 v67, v67, v159, v197
	v_fma_f32 v68, v68, v160, v198
	v_fma_f32 v69, v69, v161, v199
	v_cvt_pk_bf16_f32 v66, v66, v67
	v_cvt_pk_bf16_f32 v67, v68, v69
	ds_write_b64 v251, v[78:79] offset:25344
	ds_write_b64 v251, v[74:75] offset:25376
	ds_write_b64 v251, v[70:71] offset:25600
	ds_write_b64 v251, v[66:67] offset:25632
	s_add_u32 s8, s100, 0x80000
	s_addc_u32 s9, s101, 0
	global_store_dwordx4 v248, v[62:65], s[8:9] offset:0 sc1
	global_store_dwordx4 v248, v[58:61], s[8:9] offset:64 sc1
	global_store_dwordx4 v248, v[54:57], s[8:9] offset:512 sc1
	global_store_dwordx4 v248, v[50:53], s[8:9] offset:576 sc1
	s_nop 1
	v_mul_f32_e32 v62, v62, v216
	v_mul_f32_e32 v63, v63, v216
	v_mul_f32_e32 v64, v64, v216
	v_mul_f32_e32 v65, v65, v216
	v_fma_f32 v62, v62, v146, v162
	v_fma_f32 v63, v63, v147, v163
	v_fma_f32 v64, v64, v148, v164
	v_fma_f32 v65, v65, v149, v165
	v_cvt_pk_bf16_f32 v62, v62, v63
	v_cvt_pk_bf16_f32 v63, v64, v65
	v_mul_f32_e32 v58, v58, v216
	v_mul_f32_e32 v59, v59, v216
	v_mul_f32_e32 v60, v60, v216
	v_mul_f32_e32 v61, v61, v216
	v_fma_f32 v58, v58, v150, v188
	v_fma_f32 v59, v59, v151, v189
	v_fma_f32 v60, v60, v152, v190
	v_fma_f32 v61, v61, v153, v191
	v_cvt_pk_bf16_f32 v58, v58, v59
	v_cvt_pk_bf16_f32 v59, v60, v61
	v_mul_f32_e32 v54, v54, v216
	v_mul_f32_e32 v55, v55, v216
	v_mul_f32_e32 v56, v56, v216
	v_mul_f32_e32 v57, v57, v216
	v_fma_f32 v54, v54, v154, v192
	v_fma_f32 v55, v55, v155, v193
	v_fma_f32 v56, v56, v156, v194
	v_fma_f32 v57, v57, v157, v195
	v_cvt_pk_bf16_f32 v54, v54, v55
	v_cvt_pk_bf16_f32 v55, v56, v57
	v_mul_f32_e32 v50, v50, v216
	v_mul_f32_e32 v51, v51, v216
	v_mul_f32_e32 v52, v52, v216
	v_mul_f32_e32 v53, v53, v216
	v_fma_f32 v50, v50, v158, v196
	v_fma_f32 v51, v51, v159, v197
	v_fma_f32 v52, v52, v160, v198
	v_fma_f32 v53, v53, v161, v199
	v_cvt_pk_bf16_f32 v50, v50, v51
	v_cvt_pk_bf16_f32 v51, v52, v53
	ds_write_b64 v252, v[62:63] offset:0
	ds_write_b64 v252, v[58:59] offset:32
	ds_write_b64 v252, v[54:55] offset:256
	ds_write_b64 v252, v[50:51] offset:288
	s_add_u32 s8, s100, 0x90000
	s_addc_u32 s9, s101, 0
	global_store_dwordx4 v248, v[46:49], s[8:9] offset:0 sc1
	global_store_dwordx4 v248, v[42:45], s[8:9] offset:64 sc1
	global_store_dwordx4 v248, v[38:41], s[8:9] offset:512 sc1
	global_store_dwordx4 v248, v[34:37], s[8:9] offset:576 sc1
	s_nop 1
	v_mul_f32_e32 v46, v46, v220
	v_mul_f32_e32 v47, v47, v220
	v_mul_f32_e32 v48, v48, v220
	v_mul_f32_e32 v49, v49, v220
	v_fma_f32 v46, v46, v146, v162
	v_fma_f32 v47, v47, v147, v163
	v_fma_f32 v48, v48, v148, v164
	v_fma_f32 v49, v49, v149, v165
	v_cvt_pk_bf16_f32 v46, v46, v47
	v_cvt_pk_bf16_f32 v47, v48, v49
	v_mul_f32_e32 v42, v42, v220
	v_mul_f32_e32 v43, v43, v220
	v_mul_f32_e32 v44, v44, v220
	v_mul_f32_e32 v45, v45, v220
	v_fma_f32 v42, v42, v150, v188
	v_fma_f32 v43, v43, v151, v189
	v_fma_f32 v44, v44, v152, v190
	v_fma_f32 v45, v45, v153, v191
	v_cvt_pk_bf16_f32 v42, v42, v43
	v_cvt_pk_bf16_f32 v43, v44, v45
	v_mul_f32_e32 v38, v38, v220
	v_mul_f32_e32 v39, v39, v220
	v_mul_f32_e32 v40, v40, v220
	v_mul_f32_e32 v41, v41, v220
	v_fma_f32 v38, v38, v154, v192
	v_fma_f32 v39, v39, v155, v193
	v_fma_f32 v40, v40, v156, v194
	v_fma_f32 v41, v41, v157, v195
	v_cvt_pk_bf16_f32 v38, v38, v39
	v_cvt_pk_bf16_f32 v39, v40, v41
	v_mul_f32_e32 v34, v34, v220
	v_mul_f32_e32 v35, v35, v220
	v_mul_f32_e32 v36, v36, v220
	v_mul_f32_e32 v37, v37, v220
	v_fma_f32 v34, v34, v158, v196
	v_fma_f32 v35, v35, v159, v197
	v_fma_f32 v36, v36, v160, v198
	v_fma_f32 v37, v37, v161, v199
	v_cvt_pk_bf16_f32 v34, v34, v35
	v_cvt_pk_bf16_f32 v35, v36, v37
	ds_write_b64 v252, v[46:47] offset:8448
	ds_write_b64 v252, v[42:43] offset:8480
	ds_write_b64 v252, v[38:39] offset:8704
	ds_write_b64 v252, v[34:35] offset:8736
	s_add_u32 s8, s100, 0xa0000
	s_addc_u32 s9, s101, 0
	global_store_dwordx4 v248, v[30:33], s[8:9] offset:0 sc1
	global_store_dwordx4 v248, v[26:29], s[8:9] offset:64 sc1
	global_store_dwordx4 v248, v[22:25], s[8:9] offset:512 sc1
	global_store_dwordx4 v248, v[18:21], s[8:9] offset:576 sc1
	s_nop 1
	v_mul_f32_e32 v30, v30, v240
	v_mul_f32_e32 v31, v31, v240
	v_mul_f32_e32 v32, v32, v240
	v_mul_f32_e32 v33, v33, v240
	v_fma_f32 v30, v30, v146, v162
	v_fma_f32 v31, v31, v147, v163
	v_fma_f32 v32, v32, v148, v164
	v_fma_f32 v33, v33, v149, v165
	v_cvt_pk_bf16_f32 v30, v30, v31
	v_cvt_pk_bf16_f32 v31, v32, v33
	v_mul_f32_e32 v26, v26, v240
	v_mul_f32_e32 v27, v27, v240
	v_mul_f32_e32 v28, v28, v240
	v_mul_f32_e32 v29, v29, v240
	v_fma_f32 v26, v26, v150, v188
	v_fma_f32 v27, v27, v151, v189
	v_fma_f32 v28, v28, v152, v190
	v_fma_f32 v29, v29, v153, v191
	v_cvt_pk_bf16_f32 v26, v26, v27
	v_cvt_pk_bf16_f32 v27, v28, v29
	v_mul_f32_e32 v22, v22, v240
	v_mul_f32_e32 v23, v23, v240
	v_mul_f32_e32 v24, v24, v240
	v_mul_f32_e32 v25, v25, v240
	v_fma_f32 v22, v22, v154, v192
	v_fma_f32 v23, v23, v155, v193
	v_fma_f32 v24, v24, v156, v194
	v_fma_f32 v25, v25, v157, v195
	v_cvt_pk_bf16_f32 v22, v22, v23
	v_cvt_pk_bf16_f32 v23, v24, v25
	v_mul_f32_e32 v18, v18, v240
	v_mul_f32_e32 v19, v19, v240
	v_mul_f32_e32 v20, v20, v240
	v_mul_f32_e32 v21, v21, v240
	v_fma_f32 v18, v18, v158, v196
	v_fma_f32 v19, v19, v159, v197
	v_fma_f32 v20, v20, v160, v198
	v_fma_f32 v21, v21, v161, v199
	v_cvt_pk_bf16_f32 v18, v18, v19
	v_cvt_pk_bf16_f32 v19, v20, v21
	ds_write_b64 v252, v[30:31] offset:16896
	ds_write_b64 v252, v[26:27] offset:16928
	ds_write_b64 v252, v[22:23] offset:17152
	ds_write_b64 v252, v[18:19] offset:17184
	s_add_u32 s8, s100, 0xb0000
	s_addc_u32 s9, s101, 0
	global_store_dwordx4 v248, v[14:17], s[8:9] offset:0 sc1
	global_store_dwordx4 v248, v[10:13], s[8:9] offset:64 sc1
	global_store_dwordx4 v248, v[6:9], s[8:9] offset:512 sc1
	global_store_dwordx4 v248, v[2:5], s[8:9] offset:576 sc1
	s_nop 1
	v_mul_f32_e32 v14, v14, v244
	v_mul_f32_e32 v15, v15, v244
	v_mul_f32_e32 v16, v16, v244
	v_mul_f32_e32 v17, v17, v244
	v_fma_f32 v14, v14, v146, v162
	v_fma_f32 v15, v15, v147, v163
	v_fma_f32 v16, v16, v148, v164
	v_fma_f32 v17, v17, v149, v165
	v_cvt_pk_bf16_f32 v14, v14, v15
	v_cvt_pk_bf16_f32 v15, v16, v17
	v_mul_f32_e32 v10, v10, v244
	v_mul_f32_e32 v11, v11, v244
	v_mul_f32_e32 v12, v12, v244
	v_mul_f32_e32 v13, v13, v244
	v_fma_f32 v10, v10, v150, v188
	v_fma_f32 v11, v11, v151, v189
	v_fma_f32 v12, v12, v152, v190
	v_fma_f32 v13, v13, v153, v191
	v_cvt_pk_bf16_f32 v10, v10, v11
	v_cvt_pk_bf16_f32 v11, v12, v13
	v_mul_f32_e32 v6, v6, v244
	v_mul_f32_e32 v7, v7, v244
	v_mul_f32_e32 v8, v8, v244
	v_mul_f32_e32 v9, v9, v244
	v_fma_f32 v6, v6, v154, v192
	v_fma_f32 v7, v7, v155, v193
	v_fma_f32 v8, v8, v156, v194
	v_fma_f32 v9, v9, v157, v195
	v_cvt_pk_bf16_f32 v6, v6, v7
	v_cvt_pk_bf16_f32 v7, v8, v9
	v_mul_f32_e32 v2, v2, v244
	v_mul_f32_e32 v3, v3, v244
	v_mul_f32_e32 v4, v4, v244
	v_mul_f32_e32 v5, v5, v244
	v_fma_f32 v2, v2, v158, v196
	v_fma_f32 v3, v3, v159, v197
	v_fma_f32 v4, v4, v160, v198
	v_fma_f32 v5, v5, v161, v199
	v_cvt_pk_bf16_f32 v2, v2, v3
	v_cvt_pk_bf16_f32 v3, v4, v5
	ds_write_b64 v252, v[14:15] offset:25344
	ds_write_b64 v252, v[10:11] offset:25376
	ds_write_b64 v252, v[6:7] offset:25600
	ds_write_b64 v252, v[2:3] offset:25632
	v_lshl_add_u32 v249, v236, 4, v235
	v_lshrrev_b32_e32 v250, 5, v249
	v_and_b32_e32 v249, 31, v249
	v_lshlrev_b32_e32 v249, 4, v249
	v_lshl_add_u32 v250, s3, 5, v250
	v_mul_u32_u24_e32 v251, 0x210, v250
	v_add_u32_e32 v251, v251, v249
	v_lshl_add_u32 v248, v250, 11, v249
	v_readlane_b32 s12, v255, 9
	v_readlane_b32 s13, v255, 10
	s_lshl_b32 s2, s17, 19
	s_lshl_b32 s8, s48, 9
	s_add_i32 s2, s2, s8
	s_add_u32 s12, s12, s2
	s_addc_u32 s13, s13, 0
	s_waitcnt lgkmcnt(0)
	s_barrier
	ds_read_b128 v[2:5], v251 offset:0
	ds_read_b128 v[6:9], v251 offset:1056
	ds_read_b128 v[10:13], v251 offset:2112
	ds_read_b128 v[14:17], v251 offset:3168
	ds_read_b128 v[18:21], v251 offset:4224
	ds_read_b128 v[22:25], v251 offset:5280
	ds_read_b128 v[26:29], v251 offset:6336
	ds_read_b128 v[30:33], v251 offset:7392
	ds_read_b128 v[34:37], v251 offset:8448
	ds_read_b128 v[38:41], v251 offset:9504
	ds_read_b128 v[42:45], v251 offset:10560
	ds_read_b128 v[46:49], v251 offset:11616
	ds_read_b128 v[50:53], v251 offset:12672
	ds_read_b128 v[54:57], v251 offset:13728
	ds_read_b128 v[58:61], v251 offset:14784
	ds_read_b128 v[62:65], v251 offset:15840
	s_waitcnt lgkmcnt(15)
	global_store_dwordx4 v248, v[2:5], s[12:13]
	s_waitcnt lgkmcnt(14)
	s_add_u32 s14, s12, 0x1000
	s_addc_u32 s15, s13, 0
	global_store_dwordx4 v248, v[6:9], s[14:15]
	s_waitcnt lgkmcnt(13)
	s_add_u32 s14, s12, 0x2000
	s_addc_u32 s15, s13, 0
	global_store_dwordx4 v248, v[10:13], s[14:15]
	s_waitcnt lgkmcnt(12)
	s_add_u32 s14, s12, 0x3000
	s_addc_u32 s15, s13, 0
	global_store_dwordx4 v248, v[14:17], s[14:15]
	s_waitcnt lgkmcnt(11)
	s_add_u32 s14, s12, 0x4000
	s_addc_u32 s15, s13, 0
	global_store_dwordx4 v248, v[18:21], s[14:15]
	s_waitcnt lgkmcnt(10)
	s_add_u32 s14, s12, 0x5000
	s_addc_u32 s15, s13, 0
	global_store_dwordx4 v248, v[22:25], s[14:15]
	s_waitcnt lgkmcnt(9)
	s_add_u32 s14, s12, 0x6000
	s_addc_u32 s15, s13, 0
	global_store_dwordx4 v248, v[26:29], s[14:15]
	s_waitcnt lgkmcnt(8)
	s_add_u32 s14, s12, 0x7000
	s_addc_u32 s15, s13, 0
	global_store_dwordx4 v248, v[30:33], s[14:15]
	s_waitcnt lgkmcnt(7)
	s_add_u32 s14, s12, 0x8000
	s_addc_u32 s15, s13, 0
	global_store_dwordx4 v248, v[34:37], s[14:15]
	s_waitcnt lgkmcnt(6)
	s_add_u32 s14, s12, 0x9000
	s_addc_u32 s15, s13, 0
	global_store_dwordx4 v248, v[38:41], s[14:15]
	s_waitcnt lgkmcnt(5)
	s_add_u32 s14, s12, 0xa000
	s_addc_u32 s15, s13, 0
	global_store_dwordx4 v248, v[42:45], s[14:15]
	s_waitcnt lgkmcnt(4)
	s_add_u32 s14, s12, 0xb000
	s_addc_u32 s15, s13, 0
	global_store_dwordx4 v248, v[46:49], s[14:15]
	s_waitcnt lgkmcnt(3)
	s_add_u32 s14, s12, 0xc000
	s_addc_u32 s15, s13, 0
	global_store_dwordx4 v248, v[50:53], s[14:15]
	s_waitcnt lgkmcnt(2)
	s_add_u32 s14, s12, 0xd000
	s_addc_u32 s15, s13, 0
	global_store_dwordx4 v248, v[54:57], s[14:15]
	s_waitcnt lgkmcnt(1)
	s_add_u32 s14, s12, 0xe000
	s_addc_u32 s15, s13, 0
	global_store_dwordx4 v248, v[58:61], s[14:15]
	s_waitcnt lgkmcnt(0)
	s_add_u32 s14, s12, 0xf000
	s_addc_u32 s15, s13, 0
	global_store_dwordx4 v248, v[62:65], s[14:15]
	s_branch .LBB0_561
